# fft1 loop: prefetch waited once after the tile MFMAs and before its stores (head vmcnt waits no longer drain the stores); (1+scale) deferred to first use
# speedup vs baseline: 1.0075x; 1.0075x over previous
.LBB0_745:
	s_or_b64 exec, exec, s[4:5]
	s_cmpk_lt_i32 s2, 0x1000
	s_movk_i32 s3, 0x1000
	s_waitcnt lgkmcnt(0)
	s_barrier
	s_cbranch_scc0 .LBB0_767
	v_lshrrev_b32_e32 v3, 4, v2
	v_and_b32_e32 v5, 48, v3
	v_lshrrev_b32_e32 v6, 3, v2
	v_lshlrev_b32_e32 v24, 3, v2
	v_and_or_b32 v5, v6, 8, v5
	v_lshrrev_b32_e32 v5, 1, v5
	v_bfe_u32 v6, v24, 5, 2
	v_or_b32_e32 v5, v5, v6
	v_add_u32_e32 v14, 32, v3
	v_lshlrev_b32_e32 v75, 9, v5
	v_lshlrev_b32_e32 v5, 4, v2
	v_and_b32_e32 v7, 0x70, v14
	v_lshlrev_b32_e32 v8, 1, v14
	v_and_b32_e32 v25, 3, v4
	v_bfe_u32 v26, v2, 5, 1
	v_and_b32_e32 v81, 48, v5
	v_and_or_b32 v7, v8, 8, v7
	v_lshrrev_b32_e32 v4, 5, v2
	v_and_b32_e32 v30, 0xc0, v5
	v_bfe_u32 v5, v2, 4, 2
	v_lshlrev_b32_e32 v32, 3, v26
	v_lshlrev_b32_e32 v33, 4, v25
	v_lshrrev_b32_e32 v7, 1, v7
	v_and_or_b32 v31, v4, 4, v5
	v_or_b32_e32 v4, 48, v32
	v_and_or_b32 v46, v2, 15, v33
	v_and_b32_e32 v47, 16, v2
	v_or_b32_e32 v6, v7, v6
	v_mad_u32_u24 v4, v4, v46, v47
	v_lshlrev_b32_e32 v83, 9, v6
	v_lshlrev_b32_e32 v6, 1, v2
	v_lshlrev_b32_e32 v5, 8, v4
	v_add_u32_e32 v4, v4, v46
	v_and_b32_e32 v29, 32, v6
	v_lshlrev_b32_e32 v6, 8, v4
	v_add_u32_e32 v4, v4, v46
	v_lshlrev_b32_e32 v7, 8, v4
	v_add_u32_e32 v4, v4, v46
	v_lshlrev_b32_e32 v8, 8, v4
	v_add_u32_e32 v4, v4, v46
	v_lshlrev_b32_e32 v9, 8, v4
	v_add_u32_e32 v4, v4, v46
	v_lshlrev_b32_e32 v10, 8, v4
	v_add_u32_e32 v4, v4, v46
	v_lshlrev_b32_e32 v11, 8, v4
	v_add_u32_e32 v12, v4, v46
	v_and_b32_e32 v5, 0x3800, v5
	v_and_b32_e32 v6, 0x3f00, v6
	v_and_b32_e32 v7, 0x3e00, v7
	v_and_b32_e32 v8, 0x3f00, v8
	v_and_b32_e32 v9, 0x3c00, v9
	v_and_b32_e32 v10, 0x3f00, v10
	v_and_b32_e32 v11, 0x3e00, v11
	v_lshlrev_b32_e32 v4, 8, v12
	v_add_u32_e32 v5, s8, v5
	v_add_u32_e32 v6, s8, v6
	v_add_u32_e32 v7, s8, v7
	v_add_u32_e32 v8, s8, v8
	v_add_u32_e32 v9, s8, v9
	v_add_u32_e32 v10, s8, v10
	v_add_u32_e32 v11, s8, v11
	v_and_b32_e32 v4, 0x3f00, v4
	v_add_u32_e32 v13, s8, v4
	ds_read_b32 v4, v5
	ds_read_b32 v5, v6
	ds_read_b32 v6, v7
	ds_read_b32 v7, v8
	ds_read_b32 v8, v9
	ds_read_b32 v9, v10
	ds_read_b32 v10, v11
	ds_read_b32 v11, v13
	s_mov_b32 s0, 0x3e000000
	s_waitcnt lgkmcnt(6)
	v_pk_mul_f32 v[4:5], v[4:5], s[0:1] op_sel_hi:[1,0]
	s_add_u32 s30, s48, 0x1000
	v_cvt_pk_bf16_f32 v34, v4, v5
	s_waitcnt lgkmcnt(4)
	v_pk_mul_f32 v[4:5], v[6:7], s[0:1] op_sel_hi:[1,0]
	s_addc_u32 s31, s49, 0
	v_cvt_pk_bf16_f32 v35, v4, v5
	s_waitcnt lgkmcnt(2)
	v_pk_mul_f32 v[4:5], v[8:9], s[0:1] op_sel_hi:[1,0]
	s_add_u32 s46, s56, 0x2876000
	v_cvt_pk_bf16_f32 v36, v4, v5
	s_waitcnt lgkmcnt(0)
	v_pk_mul_f32 v[4:5], v[10:11], s[0:1] op_sel_hi:[1,0]
	s_movk_i32 s1, 0xffe9
	v_cvt_pk_bf16_f32 v37, v4, v5
	v_mad_i32_i24 v4, v46, s1, v12
	v_lshlrev_b32_e32 v5, 8, v4
	v_add_u32_e32 v4, v4, v46
	v_lshlrev_b32_e32 v6, 8, v4
	v_add_u32_e32 v4, v4, v46
	v_lshlrev_b32_e32 v7, 8, v4
	v_add_u32_e32 v4, v4, v46
	v_lshlrev_b32_e32 v8, 8, v4
	v_add_u32_e32 v4, v4, v46
	v_lshlrev_b32_e32 v9, 8, v4
	v_add_u32_e32 v4, v4, v46
	v_lshlrev_b32_e32 v10, 8, v4
	v_add_u32_e32 v4, v4, v46
	v_lshlrev_b32_e32 v11, 8, v4
	v_add_u32_e32 v12, v4, v46
	v_and_b32_e32 v5, 0x3800, v5
	v_and_b32_e32 v6, 0x3f00, v6
	v_and_b32_e32 v7, 0x3e00, v7
	v_and_b32_e32 v8, 0x3f00, v8
	v_and_b32_e32 v9, 0x3c00, v9
	v_and_b32_e32 v10, 0x3f00, v10
	v_and_b32_e32 v11, 0x3e00, v11
	v_lshlrev_b32_e32 v4, 8, v12
	v_add_u32_e32 v5, s8, v5
	v_add_u32_e32 v6, s8, v6
	v_add_u32_e32 v7, s8, v7
	v_add_u32_e32 v8, s8, v8
	v_add_u32_e32 v9, s8, v9
	v_add_u32_e32 v10, s8, v10
	v_add_u32_e32 v11, s8, v11
	v_and_b32_e32 v4, 0x3f00, v4
	v_add_u32_e32 v13, s8, v4
	ds_read_b32 v4, v5
	ds_read_b32 v5, v6
	ds_read_b32 v6, v7
	ds_read_b32 v7, v8
	ds_read_b32 v8, v9
	ds_read_b32 v9, v10
	ds_read_b32 v10, v11
	ds_read_b32 v11, v13
	s_waitcnt lgkmcnt(6)
	v_pk_mul_f32 v[4:5], v[4:5], s[0:1] op_sel_hi:[1,0]
	s_addc_u32 s47, s57, 0
	v_cvt_pk_bf16_f32 v38, v4, v5
	s_waitcnt lgkmcnt(4)
	v_pk_mul_f32 v[4:5], v[6:7], s[0:1] op_sel_hi:[1,0]
	v_lshlrev_b32_e32 v85, 6, v3
	v_cvt_pk_bf16_f32 v39, v4, v5
	s_waitcnt lgkmcnt(2)
	v_pk_mul_f32 v[4:5], v[8:9], s[0:1] op_sel_hi:[1,0]
	s_bfe_u32 s5, s2, 0x60003
	v_cvt_pk_bf16_f32 v40, v4, v5
	s_waitcnt lgkmcnt(0)
	v_pk_mul_f32 v[4:5], v[10:11], s[0:1] op_sel_hi:[1,0]
	s_lshl_b32 s48, s2, 7
	v_cvt_pk_bf16_f32 v41, v4, v5
	v_mad_i32_i24 v4, v46, s1, v12
	v_lshlrev_b32_e32 v5, 8, v4
	v_and_b32_e32 v5, 0x3800, v5
	v_add_u32_e32 v4, v4, v46
	v_add_u32_e32 v16, s8, v5
	v_lshlrev_b32_e32 v5, 8, v4
	v_and_b32_e32 v5, 0x3f00, v5
	v_add_u32_e32 v4, v4, v46
	v_add_u32_e32 v17, s8, v5
	v_lshlrev_b32_e32 v5, 8, v4
	v_and_b32_e32 v5, 0x3e00, v5
	v_add_u32_e32 v4, v4, v46
	v_add_u32_e32 v18, s8, v5
	v_lshlrev_b32_e32 v5, 8, v4
	v_add_u32_e32 v4, v4, v46
	v_and_b32_e32 v5, 0x3f00, v5
	v_add_u32_e32 v21, v4, v46
	v_add_u32_e32 v19, s8, v5
	v_lshlrev_b32_e32 v5, 8, v4
	v_lshlrev_b32_e32 v4, 8, v21
	s_ashr_i32 s1, s2, 9
	v_and_b32_e32 v4, 0x3f00, v4
	s_lshl_b32 s4, s1, 12
	v_add_u32_e32 v22, s8, v4
	v_or_b32_e32 v4, s4, v85
	v_and_b32_e32 v5, 0x3c00, v5
	v_or_b32_e32 v4, s5, v4
	v_add_u32_e32 v20, s8, v5
	v_ashrrev_i32_e32 v5, 31, v4
	v_lshlrev_b64 v[4:5], 11, v[4:5]
	s_and_b32 s6, s48, 0x380
	v_and_b32_e32 v74, 0x78, v24
	s_mov_b32 s37, 0
	v_lshl_add_u64 v[4:5], s[20:21], 0, v[4:5]
	s_lshl_b32 s36, s6, 1
	v_lshl_add_u64 v[4:5], v[4:5], 0, s[36:37]
	v_mov_b32_e32 v77, 0
	v_lshlrev_b32_e32 v76, 1, v74
	v_lshlrev_b32_e32 v87, 6, v14
	v_lshl_add_u64 v[12:13], v[4:5], 0, v[76:77]
	v_add_u32_e32 v4, s4, v87
	v_or_b32_e32 v4, s5, v4
	v_ashrrev_i32_e32 v5, 31, v4
	v_lshlrev_b64 v[4:5], 11, v[4:5]
	v_lshl_add_u64 v[4:5], s[20:21], 0, v[4:5]
	v_lshl_add_u64 v[4:5], v[4:5], 0, s[36:37]
	s_mul_hi_i32 s5, s1, 0x6000
	s_mulk_i32 s1, 0x6000
	v_lshl_add_u64 v[14:15], v[4:5], 0, v[76:77]
	v_or_b32_e32 v4, s6, v74
	s_add_u32 s4, s46, s1
	s_addc_u32 s5, s47, s5
	v_lshlrev_b32_e32 v76, 2, v4
	v_add_u32_e32 v21, v21, v46
	v_lshl_add_u64 v[8:9], s[4:5], 0, v[76:77]
	v_lshlrev_b32_e32 v23, 8, v21
	s_mov_b64 s[28:29], 0x1000
	v_add_co_u32_e32 v4, vcc, s3, v8
	v_and_b32_e32 v23, 0x3e00, v23
	v_add_lshl_u32 v21, v21, v46, 8
	v_addc_co_u32_e32 v5, vcc, 0, v9, vcc
	v_lshl_add_u64 v[8:9], v[8:9], 0, s[28:29]
	v_add_u32_e32 v23, s8, v23
	v_and_b32_e32 v21, 0x3f00, v21
	global_load_dwordx4 v[4:7], v[4:5], off
	v_add_u32_e32 v42, s8, v21
	global_load_dwordx4 v[8:11], v[8:9], off offset:16
	ds_read_b32 v16, v16
	ds_read_b32 v17, v17
	ds_read_b32 v18, v18
	ds_read_b32 v19, v19
	ds_read_b32 v20, v20
	ds_read_b32 v21, v22
	ds_read_b32 v22, v23
	ds_read_b32 v23, v42
	global_load_dwordx4 v[66:69], v[12:13], off
	global_load_dwordx4 v[70:73], v[14:15], off
	global_load_dwordx4 v[50:53], v76, s[30:31] offset:16
	global_load_dwordx4 v[54:57], v76, s[30:31]
	global_load_dwordx4 v[58:61], v76, s[4:5] offset:16
	global_load_dwordx4 v[62:65], v76, s[4:5]
	s_waitcnt lgkmcnt(6)
	v_pk_mul_f32 v[16:17], v[16:17], s[0:1] op_sel_hi:[1,0]
	v_lshrrev_b32_e32 v27, 8, v2
	v_cvt_pk_bf16_f32 v42, v16, v17
	s_waitcnt lgkmcnt(4)
	v_pk_mul_f32 v[16:17], v[18:19], s[0:1] op_sel_hi:[1,0]
	v_lshlrev_b32_e32 v28, 10, v27
	v_cvt_pk_bf16_f32 v43, v16, v17
	s_waitcnt lgkmcnt(2)
	v_pk_mul_f32 v[16:17], v[20:21], s[0:1] op_sel_hi:[1,0]
	v_and_b32_e32 v2, 31, v2
	v_cvt_pk_bf16_f32 v44, v16, v17
	s_waitcnt lgkmcnt(0)
	v_pk_mul_f32 v[16:17], v[22:23], s[0:1] op_sel_hi:[1,0]
	v_lshlrev_b32_e32 v76, 7, v27
	v_cvt_pk_bf16_f32 v45, v16, v17
	v_mad_u32_u24 v16, v46, v32, v47
	v_lshlrev_b32_e32 v17, 8, v16
	v_add_u32_e32 v16, v16, v46
	v_lshlrev_b32_e32 v18, 8, v16
	v_add_u32_e32 v16, v16, v46
	v_lshlrev_b32_e32 v19, 8, v16
	v_add_u32_e32 v16, v16, v46
	v_lshlrev_b32_e32 v20, 8, v16
	v_add_u32_e32 v16, v16, v46
	v_lshlrev_b32_e32 v12, 8, v16
	v_and_b32_e32 v12, 0x3c00, v12
	v_add_u32_e32 v21, s8, v12
	v_add_u32_e32 v12, v16, v46
	v_lshlrev_b32_e32 v13, 8, v12
	v_and_b32_e32 v13, 0x3f00, v13
	v_add_u32_e32 v12, v12, v46
	v_and_b32_e32 v17, 0x3800, v17
	v_and_b32_e32 v18, 0x3f00, v18
	v_and_b32_e32 v19, 0x3e00, v19
	v_add_u32_e32 v22, s8, v13
	v_lshlrev_b32_e32 v13, 8, v12
	v_add_lshl_u32 v12, v12, v46, 8
	v_add_u32_e32 v17, s8, v17
	v_add_u32_e32 v18, s8, v18
	v_add_u32_e32 v19, s8, v19
	v_and_b32_e32 v20, 0x3f00, v20
	v_and_b32_e32 v13, 0x3e00, v13
	v_and_b32_e32 v12, 0x3f00, v12
	v_add_u32_e32 v20, s8, v20
	v_add_u32_e32 v23, s8, v13
	v_add_u32_e32 v32, s8, v12
	ds_read_b32 v12, v17
	ds_read_b32 v13, v18
	ds_read_b32 v14, v19
	ds_read_b32 v15, v20
	ds_read_b32 v16, v21
	ds_read_b32 v17, v22
	ds_read_b32 v18, v23
	ds_read_b32 v19, v32
	s_waitcnt lgkmcnt(6)
	v_pk_mul_f32 v[12:13], v[12:13], s[0:1] op_sel_hi:[1,0]
	s_cmp_lg_u32 0, -1
	v_cvt_pk_bf16_f32 v46, v12, v13
	s_waitcnt lgkmcnt(4)
	v_pk_mul_f32 v[12:13], v[14:15], s[0:1] op_sel_hi:[1,0]
	v_lshl_or_b32 v89, v26, 2, v33
	v_cvt_pk_bf16_f32 v47, v12, v13
	s_waitcnt lgkmcnt(2)
	v_pk_mul_f32 v[12:13], v[16:17], s[0:1] op_sel_hi:[1,0]
	s_cselect_b32 s36, 0, 0
	v_cvt_pk_bf16_f32 v48, v12, v13
	s_waitcnt lgkmcnt(0)
	v_pk_mul_f32 v[12:13], v[18:19], s[0:1] op_sel_hi:[1,0]
	s_mov_b64 s[4:5], 0xecb0000
	v_or_b32_e32 v93, 1, v89
	v_or_b32_e32 v95, 2, v89
	v_or_b32_e32 v106, 3, v89
	v_or_b32_e32 v107, 8, v89
	v_or_b32_e32 v108, 9, v89
	v_or_b32_e32 v109, 10, v89
	v_or_b32_e32 v110, 11, v89
	v_cvt_pk_bf16_f32 v49, v12, v13
	v_cmp_ne_u32_e64 s[0:1], 3, v25
	v_lshl_add_u32 v91, v31, 6, 0
	v_lshlrev_b32_e32 v80, 7, v89
	v_cmp_gt_u32_e64 s[6:7], 33, v93
	v_lshlrev_b32_e32 v82, 7, v93
	v_cmp_gt_u32_e64 s[8:9], 33, v95
	v_lshlrev_b32_e32 v84, 7, v95
	v_cmp_gt_u32_e64 s[10:11], 33, v106
	v_lshlrev_b32_e32 v86, 7, v106
	v_cmp_gt_u32_e64 s[12:13], 33, v107
	v_lshlrev_b32_e32 v88, 7, v107
	v_cmp_gt_u32_e64 s[14:15], 33, v108
	s_waitcnt vmcnt(7)
	v_pk_add_f32 v[96:97], v[6:7], 1.0 op_sel_hi:[1,0]
	v_and_b32_e32 v6, 0x118, v24
	v_pk_add_f32 v[98:99], v[4:5], 1.0 op_sel_hi:[1,0]
	v_lshl_add_u64 v[4:5], s[56:57], 0, v[76:77]
	v_lshlrev_b32_e32 v76, 1, v2
	v_or3_b32 v2, v28, v29, v6
	v_lshl_add_u64 v[4:5], v[4:5], 0, v[76:77]
	v_add3_u32 v111, v30, s36, v2
	v_lshl_add_u32 v2, v3, 2, 0
	s_waitcnt vmcnt(6)
	v_pk_add_f32 v[100:101], v[10:11], 1.0 op_sel_hi:[1,0]
	v_pk_add_f32 v[102:103], v[8:9], 1.0 op_sel_hi:[1,0]
	v_lshl_add_u64 v[78:79], v[4:5], 0, s[4:5]
	v_cmp_gt_u32_e64 s[4:5], 33, v89
	v_lshlrev_b32_e32 v90, 7, v108
	v_cmp_gt_u32_e64 s[16:17], 33, v109
	v_lshlrev_b32_e32 v92, 7, v109
	v_cmp_gt_u32_e64 s[18:19], 33, v110
	v_lshlrev_b32_e32 v94, 7, v110
	s_lshl_b32 s49, s33, 7
	v_add_u32_e32 v112, 0x14080, v2
	v_lshlrev_b32_e32 v76, 1, v74
	s_mov_b32 s42, s2
	s_mov_b32 s62, 0
	s_waitcnt vmcnt(0)
	s_branch .LBB0_748
.Lfft1_skip:
	s_or_b64 exec, exec, s[40:41]
	s_waitcnt vmcnt(0)
	v_pk_add_f32 v[100:101], v[132:133], 1.0 op_sel_hi:[1,0]
	v_pk_add_f32 v[96:97], v[128:129], 1.0 op_sel_hi:[1,0]
	v_pk_add_f32 v[98:99], v[126:127], 1.0 op_sel_hi:[1,0]
	v_pk_add_f32 v[102:103], v[130:131], 1.0 op_sel_hi:[1,0]
	s_branch .LBB0_747

.LBB0_748:
	v_add_u32_e32 v2, 0xffffff80, v112
	ds_read_b32 v2, v2
	ds_read_b32 v6, v112
	v_lshlrev_b32_e32 v4, 16, v66
	v_and_b32_e32 v5, 0xffff0000, v66
	v_lshlrev_b32_e32 v12, 16, v69
	v_and_b32_e32 v13, 0xffff0000, v69
	v_lshlrev_b32_e32 v8, 16, v67
	v_and_b32_e32 v9, 0xffff0000, v67
	v_lshlrev_b32_e32 v10, 16, v68
	v_and_b32_e32 v11, 0xffff0000, v68
	s_waitcnt lgkmcnt(1)
	v_pk_mul_f32 v[4:5], v[2:3], v[4:5] op_sel_hi:[0,1]
	v_pk_mul_f32 v[12:13], v[2:3], v[12:13] op_sel_hi:[0,1]
	v_pk_mul_f32 v[8:9], v[2:3], v[8:9] op_sel_hi:[0,1]
	v_pk_mul_f32 v[4:5], v[54:55], v[4:5]
	v_pk_mul_f32 v[2:3], v[2:3], v[10:11] op_sel_hi:[0,1]
	v_pk_mul_f32 v[10:11], v[52:53], v[12:13]
	v_pk_mul_f32 v[8:9], v[56:57], v[8:9]
	v_pk_fma_f32 v[4:5], v[98:99], v[4:5], v[62:63]
	v_pk_mul_f32 v[2:3], v[50:51], v[2:3]
	v_pk_fma_f32 v[10:11], v[100:101], v[10:11], v[60:61]
	v_pk_fma_f32 v[8:9], v[96:97], v[8:9], v[64:65]
	v_pk_fma_f32 v[12:13], v[102:103], v[2:3], v[58:59]
	v_cvt_pk_bf16_f32 v2, v4, v5
	v_cvt_pk_bf16_f32 v5, v10, v11
	v_lshlrev_b32_e32 v10, 16, v71
	v_and_b32_e32 v11, 0xffff0000, v71
	v_cvt_pk_bf16_f32 v3, v8, v9
	v_cvt_pk_bf16_f32 v4, v12, v13
	v_lshlrev_b32_e32 v8, 16, v70
	v_and_b32_e32 v9, 0xffff0000, v70
	v_lshlrev_b32_e32 v12, 16, v72
	v_and_b32_e32 v13, 0xffff0000, v72
	v_lshlrev_b32_e32 v14, 16, v73
	v_and_b32_e32 v15, 0xffff0000, v73
	s_waitcnt lgkmcnt(0)
	v_pk_mul_f32 v[10:11], v[6:7], v[10:11] op_sel_hi:[0,1]
	v_pk_mul_f32 v[8:9], v[6:7], v[8:9] op_sel_hi:[0,1]
	v_pk_mul_f32 v[10:11], v[56:57], v[10:11]
	v_pk_mul_f32 v[14:15], v[6:7], v[14:15] op_sel_hi:[0,1]
	v_pk_mul_f32 v[6:7], v[6:7], v[12:13] op_sel_hi:[0,1]
	v_pk_fma_f32 v[10:11], v[96:97], v[10:11], v[64:65]
	v_pk_mul_f32 v[6:7], v[50:51], v[6:7]
	s_lshl_b32 s43, s62, 14
	s_add_i32 s63, s42, s33
	v_pk_mul_f32 v[8:9], v[54:55], v[8:9]
	v_pk_mul_f32 v[12:13], v[52:53], v[14:15]
	v_pk_fma_f32 v[14:15], v[102:103], v[6:7], v[58:59]
	v_cvt_pk_bf16_f32 v7, v10, v11
	v_add_u32_e32 v10, s43, v91
	s_cmpk_gt_i32 s63, 0xfff
	v_pk_fma_f32 v[8:9], v[98:99], v[8:9], v[62:63]
	v_pk_fma_f32 v[12:13], v[100:101], v[12:13], v[60:61]
	v_add3_u32 v11, v10, v75, v81
	s_cselect_b64 s[38:39], -1, 0
	v_cvt_pk_bf16_f32 v6, v8, v9
	v_cvt_pk_bf16_f32 v8, v14, v15
	v_cvt_pk_bf16_f32 v9, v12, v13
	ds_write_b128 v11, v[2:5]
	v_add3_u32 v2, v10, v83, v81
	s_and_b64 vcc, exec, s[38:39]
	ds_write_b128 v2, v[6:9]
	s_waitcnt lgkmcnt(0)
	s_barrier
	s_cbranch_vccnz .LBB0_750
	s_ashr_i32 s40, s63, 9
	s_lshl_b32 s41, s40, 12
	v_or_b32_e32 v2, s41, v85
	s_bfe_u32 s44, s63, 0x60003
	v_or_b32_e32 v2, s44, v2
	v_ashrrev_i32_e32 v3, 31, v2
	s_add_i32 s36, s49, s48
	v_lshlrev_b64 v[2:3], 11, v[2:3]
	s_and_b32 s45, s36, 0x380
	v_lshl_add_u64 v[2:3], s[20:21], 0, v[2:3]
	s_lshl_b32 s36, s45, 1
	v_lshl_add_u64 v[2:3], v[2:3], 0, s[36:37]
	v_lshl_add_u64 v[10:11], v[2:3], 0, v[76:77]
	v_add_u32_e32 v2, s41, v87
	v_or_b32_e32 v2, s44, v2
	v_ashrrev_i32_e32 v3, 31, v2
	v_lshlrev_b64 v[2:3], 11, v[2:3]
	v_lshl_add_u64 v[2:3], s[20:21], 0, v[2:3]
	v_lshl_add_u64 v[2:3], v[2:3], 0, s[36:37]
	s_mul_hi_i32 s36, s40, 0x6000
	s_mulk_i32 s40, 0x6000
	v_lshl_add_u64 v[12:13], v[2:3], 0, v[76:77]
	v_or_b32_e32 v2, s45, v74
	s_add_u32 s40, s46, s40
	s_addc_u32 s41, s47, s36
	v_lshlrev_b32_e32 v2, 2, v2
	v_mov_b32_e32 v3, v77
	v_lshl_add_u64 v[6:7], s[40:41], 0, v[2:3]
	global_load_dwordx4 v[50:53], v2, s[30:31] offset:16
	global_load_dwordx4 v[54:57], v2, s[30:31]
	global_load_dwordx4 v[58:61], v2, s[40:41] offset:16
	global_load_dwordx4 v[62:65], v2, s[40:41]
	v_add_co_u32_e32 v2, vcc, s3, v6
	s_nop 1
	v_addc_co_u32_e32 v3, vcc, 0, v7, vcc
	global_load_dwordx4 v[126:129], v[2:3], off
	v_lshl_add_u64 v[6:7], v[6:7], 0, s[28:29]
	global_load_dwordx4 v[130:133], v[6:7], off offset:16
	s_nop 0
	global_load_dwordx4 v[66:69], v[10:11], off
	global_load_dwordx4 v[70:73], v[12:13], off
.LBB0_750:
	s_and_saveexec_b64 s[40:41], s[0:1]
	s_cbranch_execz .Lfft1_skip
	v_add_u32_e32 v30, s43, v111
	ds_read_b64_tr_b16 v[2:3], v30 offset:0
	ds_read_b64_tr_b16 v[4:5], v30 offset:0x800
	ds_read_b64_tr_b16 v[18:19], v30 offset:0x1000
	ds_read_b64_tr_b16 v[20:21], v30 offset:0x1800
	ds_read_b64_tr_b16 v[22:23], v30 offset:0x2000
	ds_read_b64_tr_b16 v[24:25], v30 offset:0x2800
	ds_read_b64_tr_b16 v[26:27], v30 offset:0x3000
	ds_read_b64_tr_b16 v[28:29], v30 offset:0x3800
	s_waitcnt lgkmcnt(0)
	s_nop 0
	v_mfma_f32_32x32x16_bf16 v[2:17], v[46:49], v[2:5], 0
	v_mfma_f32_32x32x16_bf16 v[2:17], v[42:45], v[18:21], v[2:17]
	ds_read_b64_tr_b16 v[18:19], v30 offset:0x200
	ds_read_b64_tr_b16 v[20:21], v30 offset:0xa00
	ds_read_b64_tr_b16 v[114:115], v30 offset:0x1200
	ds_read_b64_tr_b16 v[116:117], v30 offset:0x1a00
	ds_read_b64_tr_b16 v[118:119], v30 offset:0x2200
	ds_read_b64_tr_b16 v[120:121], v30 offset:0x2a00
	ds_read_b64_tr_b16 v[122:123], v30 offset:0x3200
	v_mfma_f32_32x32x16_bf16 v[2:17], v[38:41], v[22:25], v[2:17]
	ds_read_b64_tr_b16 v[124:125], v30 offset:0x3a00
	s_waitcnt lgkmcnt(0)
	v_mfma_f32_32x32x16_bf16 v[2:17], v[34:37], v[26:29], v[2:17]
	v_mfma_f32_32x32x16_bf16 v[18:33], v[46:49], v[18:21], 0
	s_ashr_i32 s44, s42, 9
	s_ashr_i32 s45, s44, 31
	s_and_b32 s36, s48, 0x380
	s_bfe_u32 s60, s42, 0x60003
	s_lshl_b64 s[42:43], s[44:45], 13
	s_lshl_b32 s36, s36, 1
	s_or_b32 s42, s42, s60
	v_mfma_f32_32x32x16_bf16 v[18:33], v[42:45], v[114:117], v[18:33]
	v_lshl_add_u64 v[104:105], v[78:79], 0, s[36:37]
	v_mfma_f32_32x32x16_bf16 v[18:33], v[38:41], v[118:121], v[18:33]
	v_mfma_f32_32x32x16_bf16 v[18:33], v[34:37], v[122:125], v[18:33]
	s_waitcnt vmcnt(0)
	v_pk_add_f32 v[100:101], v[132:133], 1.0 op_sel_hi:[1,0]
	v_pk_add_f32 v[96:97], v[128:129], 1.0 op_sel_hi:[1,0]
	v_pk_add_f32 v[98:99], v[126:127], 1.0 op_sel_hi:[1,0]
	v_pk_add_f32 v[102:103], v[130:131], 1.0 op_sel_hi:[1,0]
	s_and_saveexec_b64 s[44:45], s[4:5]
	s_cbranch_execnz .LBB0_759
	s_or_b64 exec, exec, s[44:45]
	s_and_saveexec_b64 s[44:45], s[6:7]
	s_cbranch_execnz .LBB0_760
